# scan producers without the priority asymmetry between the two producer waves of a SIMD (immediate-only change, same placement as v12)
# speedup vs baseline: 1.0052x; 1.0052x over previous
; __device__ __forceinline__ void lds_barrier() { asm volatile("s_waitcnt lgkmcnt(0)" ::: "memory"); __builtin_amdgcn_s_barrier(); asm volatile("" ::: "memory"); }
; __device__ __forceinline__ void phase_scan2(const Params& p, int l, LAS unsigned char* lds) {
;     ...
;         if (wid >= 3) { pload(pw); pbuild(pw, lds + pw * SC_SLOT, scr, SC_NP + pw); }
;         lds_barrier();
;         for (int rd = 0; rd < NRD; ++rd) {
;             if (wid == 0) {
; #pragma unroll 1
;                 for (int q = 0; q < SC_NP; ++q) { const int c = rd * SC_NP + q; if (c < NCH) consume(c, lds + ((rd & 1) * SC_NP + q) * SC_SLOT); }
;             } else if (wid >= 3) {
;                 const int cb = (rd + 1) * SC_NP + pw, cn = cb + SC_NP;
;                 if (cb < NCH) pbuild(cb, lds + (((rd + 1) & 1) * SC_NP + pw) * SC_SLOT, scr, cn < NCH ? cn : -1);
.Lsc_producer:
	s_sub_u32 s55, s25, 1
	s_cmp_gt_u32 s25, 4
	s_cselect_b32 s0, 1, 0
	s_sub_u32 s55, s55, s0
	s_cmp_gt_u32 s25, 4
	s_cbranch_scc0 .Lsc_p_noprio
	s_setprio 0
